# grid barrier: leaders no longer bump the per-XCD generation word (nobody waits on it any more)
# baseline (speedup 1.0000x reference)
.LBB0_520:
	s_or_b64 exec, exec, s[4:5]
	s_mov_b64 s[4:5], exec
	v_mbcnt_lo_u32_b32 v0, s4, 0
	v_mbcnt_hi_u32_b32 v0, s5, v0
	v_cmp_eq_u32_e32 vcc, 0, v0
	s_waitcnt vmcnt(0)
	buffer_inv sc1
	s_and_saveexec_b64 s[6:7], vcc
	s_cbranch_execz .LBB0_522
	s_bcnt1_i32_b64 s4, s[4:5]
	v_mov_b32_e32 v0, s4
.LBB0_522:
	s_or_b64 exec, exec, s[6:7]
	s_waitcnt vmcnt(0)
